# E13: E12 + GEMM K-loop MFMAs reordered into back-to-back dependent pairs (same accumulation order)
# speedup vs baseline: 1.0010x; 1.0010x over previous
.LBB0_184:
	s_add_u32 s24, s28, 0xfffc0080
	s_addc_u32 s25, s29, -1
	s_add_i32 s67, 0, 0x10000
	s_cmp_eq_u32 s66, 12
	s_cselect_b32 s41, s57, s25
	s_cselect_b32 s40, s62, s24
	s_cselect_b32 s25, s55, s65
	s_cselect_b32 s24, s63, s64
	s_add_i32 s72, 0, 0x14000
	v_add_u32_e32 v144, s67, v159
	v_add_u32_e32 v180, s72, v159
	ds_read_b128 v[132:135], v144
	ds_read_b128 v[136:139], v144 offset:1024
	ds_read_b128 v[140:143], v144 offset:2048
	ds_read_b128 v[144:147], v144 offset:3072
	ds_read_b128 v[148:151], v180
	ds_read_b128 v[152:155], v180 offset:1024
	ds_read_b128 v[172:175], v180 offset:2048
	ds_read_b128 v[180:183], v180 offset:3072
	v_lshl_add_u64 v[252:253], s[28:29], 0, v[168:169]
	s_add_i32 m0, s84, 0xc000
	ds_read_b128 v[184:187], v246
	ds_read_b128 v[188:191], v246 offset:1024
	ds_read_b128 v[192:195], v246 offset:2048
	ds_read_b128 v[196:199], v246 offset:3072
	ds_read_b128 v[248:251], v246 offset:4096
	ds_read_b128 v[206:209], v246 offset:5120
	ds_read_b128 v[210:213], v246 offset:6144
	ds_read_b128 v[214:217], v246 offset:7168
	global_load_lds_dwordx4 v[252:253], off
	v_lshl_add_u64 v[252:253], s[28:29], 0, v[170:171]
	s_add_i32 m0, s84, 0xe000
	s_nop 0
	global_load_lds_dwordx4 v[252:253], off
	s_waitcnt vmcnt(8)
	s_waitcnt lgkmcnt(0)
	s_barrier
	s_setprio 1
	s_waitcnt lgkmcnt(0)
	v_mfma_f32_16x16x32_bf16 v[128:131], v[132:135], v[184:187], v[128:131]
	v_mfma_f32_16x16x32_bf16 v[128:131], v[136:139], v[188:191], v[128:131]
	v_mfma_f32_16x16x32_bf16 v[124:127], v[140:143], v[184:187], v[124:127]
	v_mfma_f32_16x16x32_bf16 v[124:127], v[144:147], v[188:191], v[124:127]
	v_mfma_f32_16x16x32_bf16 v[112:115], v[132:135], v[192:195], v[112:115]
	v_mfma_f32_16x16x32_bf16 v[112:115], v[136:139], v[196:199], v[112:115]
	v_mfma_f32_16x16x32_bf16 v[108:111], v[140:143], v[192:195], v[108:111]
	v_mfma_f32_16x16x32_bf16 v[108:111], v[144:147], v[196:199], v[108:111]
	v_mfma_f32_16x16x32_bf16 v[96:99], v[132:135], v[248:251], v[96:99]
	v_mfma_f32_16x16x32_bf16 v[96:99], v[136:139], v[206:209], v[96:99]
	v_mfma_f32_16x16x32_bf16 v[92:95], v[140:143], v[248:251], v[92:95]
	v_mfma_f32_16x16x32_bf16 v[92:95], v[144:147], v[206:209], v[92:95]
	v_mfma_f32_16x16x32_bf16 v[80:83], v[132:135], v[210:213], v[80:83]
	v_mfma_f32_16x16x32_bf16 v[80:83], v[136:139], v[214:217], v[80:83]
	v_mfma_f32_16x16x32_bf16 v[76:79], v[140:143], v[210:213], v[76:79]
	v_mfma_f32_16x16x32_bf16 v[76:79], v[144:147], v[214:217], v[76:79]
	s_setprio 0
	s_setprio 1
	v_mfma_f32_16x16x32_bf16 v[120:123], v[148:151], v[184:187], v[120:123]
	v_mfma_f32_16x16x32_bf16 v[120:123], v[152:155], v[188:191], v[120:123]
	v_mfma_f32_16x16x32_bf16 v[116:119], v[172:175], v[184:187], v[116:119]
	v_mfma_f32_16x16x32_bf16 v[116:119], v[180:183], v[188:191], v[116:119]
	v_mfma_f32_16x16x32_bf16 v[104:107], v[148:151], v[192:195], v[104:107]
	v_mfma_f32_16x16x32_bf16 v[104:107], v[152:155], v[196:199], v[104:107]
	v_mfma_f32_16x16x32_bf16 v[100:103], v[172:175], v[192:195], v[100:103]
	v_mfma_f32_16x16x32_bf16 v[100:103], v[180:183], v[196:199], v[100:103]
	v_mfma_f32_16x16x32_bf16 v[88:91], v[148:151], v[248:251], v[88:91]
	v_mfma_f32_16x16x32_bf16 v[88:91], v[152:155], v[206:209], v[88:91]
	v_mfma_f32_16x16x32_bf16 v[84:87], v[172:175], v[248:251], v[84:87]
	v_mfma_f32_16x16x32_bf16 v[84:87], v[180:183], v[206:209], v[84:87]
	v_mfma_f32_16x16x32_bf16 v[72:75], v[148:151], v[210:213], v[72:75]
	v_mfma_f32_16x16x32_bf16 v[72:75], v[152:155], v[214:217], v[72:75]
	v_mfma_f32_16x16x32_bf16 v[68:71], v[172:175], v[210:213], v[68:71]
	v_mfma_f32_16x16x32_bf16 v[68:71], v[180:183], v[214:217], v[68:71]
	s_setprio 0
	s_barrier
	s_add_i32 s67, s67, s3
	v_lshl_add_u64 v[252:253], s[24:25], 0, v[156:157]
	s_mov_b32 m0, s67
	ds_read_b128 v[184:187], v246 offset:16384
	ds_read_b128 v[188:191], v246 offset:17408
	ds_read_b128 v[192:195], v246 offset:18432
	ds_read_b128 v[196:199], v246 offset:19456
	ds_read_b128 v[206:209], v246 offset:20480
	ds_read_b128 v[210:213], v246 offset:21504
	ds_read_b128 v[214:217], v246 offset:22528
	ds_read_b128 v[248:251], v246 offset:23552
	global_load_lds_dwordx4 v[252:253], off
	s_add_i32 m0, s67, 0x2000
	s_add_u32 s96, s24, 0x40000
	v_lshl_add_u64 v[218:219], s[24:25], 0, v[0:1]
	s_addc_u32 s97, s25, 0
	s_add_i32 s67, s72, s3
	global_load_lds_dwordx4 v[218:219], off
	v_lshl_add_u64 v[220:221], s[96:97], 0, v[156:157]
	s_mov_b32 m0, s67
	v_lshl_add_u64 v[222:223], s[40:41], 0, v[0:1]
	global_load_lds_dwordx4 v[220:221], off
	v_lshl_add_u64 v[220:221], s[96:97], 0, v[0:1]
	s_add_i32 m0, s67, 0x2000
	s_nop 0
	global_load_lds_dwordx4 v[220:221], off
	v_lshl_add_u64 v[220:221], s[40:41], 0, v[156:157]
	s_mov_b32 m0, s84
	s_nop 0
	global_load_lds_dwordx4 v[220:221], off
	s_mov_b32 m0, s85
	s_nop 0
	global_load_lds_dwordx4 v[222:223], off
	s_waitcnt vmcnt(8)
	s_waitcnt lgkmcnt(0)
	s_barrier
	s_setprio 1
	s_waitcnt lgkmcnt(0)
	v_mfma_f32_16x16x32_bf16 v[64:67], v[132:135], v[184:187], v[64:67]
	v_mfma_f32_16x16x32_bf16 v[64:67], v[136:139], v[188:191], v[64:67]
	v_mfma_f32_16x16x32_bf16 v[60:63], v[140:143], v[184:187], v[60:63]
	v_mfma_f32_16x16x32_bf16 v[60:63], v[144:147], v[188:191], v[60:63]
	v_mfma_f32_16x16x32_bf16 v[48:51], v[132:135], v[192:195], v[48:51]
	v_mfma_f32_16x16x32_bf16 v[48:51], v[136:139], v[196:199], v[48:51]
	v_mfma_f32_16x16x32_bf16 v[44:47], v[140:143], v[192:195], v[44:47]
	v_mfma_f32_16x16x32_bf16 v[44:47], v[144:147], v[196:199], v[44:47]
	v_mfma_f32_16x16x32_bf16 v[32:35], v[132:135], v[206:209], v[32:35]
	v_mfma_f32_16x16x32_bf16 v[32:35], v[136:139], v[210:213], v[32:35]
	v_mfma_f32_16x16x32_bf16 v[28:31], v[140:143], v[206:209], v[28:31]
	v_mfma_f32_16x16x32_bf16 v[28:31], v[144:147], v[210:213], v[28:31]
	v_mfma_f32_16x16x32_bf16 v[16:19], v[132:135], v[214:217], v[16:19]
	v_mfma_f32_16x16x32_bf16 v[16:19], v[136:139], v[248:251], v[16:19]
	v_mfma_f32_16x16x32_bf16 v[12:15], v[140:143], v[214:217], v[12:15]
	v_mfma_f32_16x16x32_bf16 v[12:15], v[144:147], v[248:251], v[12:15]
	s_setprio 0
	s_setprio 1
	v_mfma_f32_16x16x32_bf16 v[56:59], v[148:151], v[184:187], v[56:59]
	v_mfma_f32_16x16x32_bf16 v[56:59], v[152:155], v[188:191], v[56:59]
	v_mfma_f32_16x16x32_bf16 v[52:55], v[172:175], v[184:187], v[52:55]
	v_mfma_f32_16x16x32_bf16 v[52:55], v[180:183], v[188:191], v[52:55]
	v_mfma_f32_16x16x32_bf16 v[40:43], v[148:151], v[192:195], v[40:43]
	v_mfma_f32_16x16x32_bf16 v[40:43], v[152:155], v[196:199], v[40:43]
	v_mfma_f32_16x16x32_bf16 v[36:39], v[172:175], v[192:195], v[36:39]
	v_mfma_f32_16x16x32_bf16 v[36:39], v[180:183], v[196:199], v[36:39]
	v_mfma_f32_16x16x32_bf16 v[24:27], v[148:151], v[206:209], v[24:27]
	v_mfma_f32_16x16x32_bf16 v[24:27], v[152:155], v[210:213], v[24:27]
	v_mfma_f32_16x16x32_bf16 v[20:23], v[172:175], v[206:209], v[20:23]
	v_mfma_f32_16x16x32_bf16 v[20:23], v[180:183], v[210:213], v[20:23]
	v_mfma_f32_16x16x32_bf16 v[8:11], v[148:151], v[214:217], v[8:11]
	v_mfma_f32_16x16x32_bf16 v[8:11], v[152:155], v[248:251], v[8:11]
	v_mfma_f32_16x16x32_bf16 v[4:7], v[172:175], v[214:217], v[4:7]
	v_mfma_f32_16x16x32_bf16 v[4:7], v[180:183], v[248:251], v[4:7]
	s_setprio 0
	s_barrier
	s_add_i32 s67, 0, 0x18000
	s_add_i32 s72, 0, 0x1c000
	v_add_u32_e32 v144, s67, v159
	v_add_u32_e32 v180, s72, v159
	ds_read_b128 v[132:135], v144
	ds_read_b128 v[136:139], v144 offset:1024
	ds_read_b128 v[140:143], v144 offset:2048
	ds_read_b128 v[144:147], v144 offset:3072
	ds_read_b128 v[148:151], v180
	ds_read_b128 v[152:155], v180 offset:1024
	ds_read_b128 v[172:175], v180 offset:2048
	ds_read_b128 v[180:183], v180 offset:3072
	s_add_u32 s40, s40, 0x40000
	s_addc_u32 s41, s41, 0
	s_mov_b32 m0, s86
	v_lshl_add_u64 v[224:225], s[40:41], 0, v[156:157]
	ds_read_b128 v[184:187], v246 offset:32768
	ds_read_b128 v[188:191], v246 offset:33792
	ds_read_b128 v[192:195], v246 offset:34816
	ds_read_b128 v[196:199], v246 offset:35840
	ds_read_b128 v[206:209], v246 offset:36864
	ds_read_b128 v[210:213], v246 offset:37888
	ds_read_b128 v[214:217], v246 offset:38912
	ds_read_b128 v[248:251], v246 offset:39936
	global_load_lds_dwordx4 v[224:225], off
	v_lshl_add_u64 v[224:225], s[40:41], 0, v[0:1]
	s_mov_b32 m0, s87
	s_nop 0
	global_load_lds_dwordx4 v[224:225], off
	s_waitcnt vmcnt(8)
	s_waitcnt lgkmcnt(0)
	s_barrier
	s_setprio 1
	s_waitcnt lgkmcnt(0)
	v_mfma_f32_16x16x32_bf16 v[128:131], v[132:135], v[184:187], v[128:131]
	v_mfma_f32_16x16x32_bf16 v[128:131], v[136:139], v[188:191], v[128:131]
	v_mfma_f32_16x16x32_bf16 v[124:127], v[140:143], v[184:187], v[124:127]
	v_mfma_f32_16x16x32_bf16 v[124:127], v[144:147], v[188:191], v[124:127]
	v_mfma_f32_16x16x32_bf16 v[112:115], v[132:135], v[192:195], v[112:115]
	v_mfma_f32_16x16x32_bf16 v[112:115], v[136:139], v[196:199], v[112:115]
	v_mfma_f32_16x16x32_bf16 v[108:111], v[140:143], v[192:195], v[108:111]
	v_mfma_f32_16x16x32_bf16 v[108:111], v[144:147], v[196:199], v[108:111]
	v_mfma_f32_16x16x32_bf16 v[96:99], v[132:135], v[206:209], v[96:99]
	v_mfma_f32_16x16x32_bf16 v[96:99], v[136:139], v[210:213], v[96:99]
	v_mfma_f32_16x16x32_bf16 v[92:95], v[140:143], v[206:209], v[92:95]
	v_mfma_f32_16x16x32_bf16 v[92:95], v[144:147], v[210:213], v[92:95]
	v_mfma_f32_16x16x32_bf16 v[80:83], v[132:135], v[214:217], v[80:83]
	v_mfma_f32_16x16x32_bf16 v[80:83], v[136:139], v[248:251], v[80:83]
	v_mfma_f32_16x16x32_bf16 v[76:79], v[140:143], v[214:217], v[76:79]
	v_mfma_f32_16x16x32_bf16 v[76:79], v[144:147], v[248:251], v[76:79]
	s_setprio 0
	s_setprio 1
	v_mfma_f32_16x16x32_bf16 v[120:123], v[148:151], v[184:187], v[120:123]
	v_mfma_f32_16x16x32_bf16 v[120:123], v[152:155], v[188:191], v[120:123]
	v_mfma_f32_16x16x32_bf16 v[116:119], v[172:175], v[184:187], v[116:119]
	v_mfma_f32_16x16x32_bf16 v[116:119], v[180:183], v[188:191], v[116:119]
	v_mfma_f32_16x16x32_bf16 v[104:107], v[148:151], v[192:195], v[104:107]
	v_mfma_f32_16x16x32_bf16 v[104:107], v[152:155], v[196:199], v[104:107]
	v_mfma_f32_16x16x32_bf16 v[100:103], v[172:175], v[192:195], v[100:103]
	v_mfma_f32_16x16x32_bf16 v[100:103], v[180:183], v[196:199], v[100:103]
	v_mfma_f32_16x16x32_bf16 v[88:91], v[148:151], v[206:209], v[88:91]
	v_mfma_f32_16x16x32_bf16 v[88:91], v[152:155], v[210:213], v[88:91]
	v_mfma_f32_16x16x32_bf16 v[84:87], v[172:175], v[206:209], v[84:87]
	v_mfma_f32_16x16x32_bf16 v[84:87], v[180:183], v[210:213], v[84:87]
	v_mfma_f32_16x16x32_bf16 v[72:75], v[148:151], v[214:217], v[72:75]
	v_mfma_f32_16x16x32_bf16 v[72:75], v[152:155], v[248:251], v[72:75]
	v_mfma_f32_16x16x32_bf16 v[68:71], v[172:175], v[214:217], v[68:71]
	v_mfma_f32_16x16x32_bf16 v[68:71], v[180:183], v[248:251], v[68:71]
	s_setprio 0
	s_barrier
	s_add_i32 s40, s67, s3
	v_lshl_add_u64 v[224:225], v[252:253], 0, s[30:31]
	s_mov_b32 m0, s40
	ds_read_b128 v[184:187], v246 offset:49152
	ds_read_b128 v[188:191], v246 offset:50176
	ds_read_b128 v[192:195], v246 offset:51200
	ds_read_b128 v[196:199], v246 offset:52224
	ds_read_b128 v[206:209], v246 offset:53248
	ds_read_b128 v[210:213], v246 offset:54272
	ds_read_b128 v[214:217], v246 offset:55296
	ds_read_b128 v[248:251], v246 offset:56320
	global_load_lds_dwordx4 v[224:225], off
	s_add_i32 m0, s40, 0x2000
	s_add_u32 s24, s24, 0x40080
	v_lshl_add_u64 v[218:219], v[218:219], 0, s[30:31]
	s_addc_u32 s25, s25, 0
	s_add_i32 s40, s72, s3
	global_load_lds_dwordx4 v[218:219], off
	v_lshl_add_u64 v[218:219], s[24:25], 0, v[156:157]
	s_mov_b32 m0, s40
	s_nop 0
	global_load_lds_dwordx4 v[218:219], off
	v_lshl_add_u64 v[218:219], s[24:25], 0, v[0:1]
	s_add_i32 m0, s40, 0x2000
	s_nop 0
	global_load_lds_dwordx4 v[218:219], off
	v_lshl_add_u64 v[218:219], v[220:221], 0, s[30:31]
	s_mov_b32 m0, s92
	s_nop 0
	global_load_lds_dwordx4 v[218:219], off
	v_lshl_add_u64 v[218:219], v[222:223], 0, s[30:31]
	s_mov_b32 m0, s93
	s_nop 0
	global_load_lds_dwordx4 v[218:219], off
	s_waitcnt vmcnt(8)
	s_waitcnt lgkmcnt(0)
	s_barrier
	s_setprio 1
	s_waitcnt lgkmcnt(0)
	v_mfma_f32_16x16x32_bf16 v[64:67], v[132:135], v[184:187], v[64:67]
	v_mfma_f32_16x16x32_bf16 v[64:67], v[136:139], v[188:191], v[64:67]
	v_mfma_f32_16x16x32_bf16 v[60:63], v[140:143], v[184:187], v[60:63]
	v_mfma_f32_16x16x32_bf16 v[60:63], v[144:147], v[188:191], v[60:63]
	v_mfma_f32_16x16x32_bf16 v[48:51], v[132:135], v[192:195], v[48:51]
	v_mfma_f32_16x16x32_bf16 v[48:51], v[136:139], v[196:199], v[48:51]
	v_mfma_f32_16x16x32_bf16 v[44:47], v[140:143], v[192:195], v[44:47]
	v_mfma_f32_16x16x32_bf16 v[44:47], v[144:147], v[196:199], v[44:47]
	v_mfma_f32_16x16x32_bf16 v[32:35], v[132:135], v[206:209], v[32:35]
	v_mfma_f32_16x16x32_bf16 v[32:35], v[136:139], v[210:213], v[32:35]
	v_mfma_f32_16x16x32_bf16 v[28:31], v[140:143], v[206:209], v[28:31]
	v_mfma_f32_16x16x32_bf16 v[28:31], v[144:147], v[210:213], v[28:31]
	v_mfma_f32_16x16x32_bf16 v[16:19], v[132:135], v[214:217], v[16:19]
	v_mfma_f32_16x16x32_bf16 v[16:19], v[136:139], v[248:251], v[16:19]
	v_mfma_f32_16x16x32_bf16 v[12:15], v[140:143], v[214:217], v[12:15]
	v_mfma_f32_16x16x32_bf16 v[12:15], v[144:147], v[248:251], v[12:15]
	s_setprio 0
	s_setprio 1
	v_mfma_f32_16x16x32_bf16 v[56:59], v[148:151], v[184:187], v[56:59]
	v_mfma_f32_16x16x32_bf16 v[56:59], v[152:155], v[188:191], v[56:59]
	v_mfma_f32_16x16x32_bf16 v[52:55], v[172:175], v[184:187], v[52:55]
	v_mfma_f32_16x16x32_bf16 v[52:55], v[180:183], v[188:191], v[52:55]
	v_mfma_f32_16x16x32_bf16 v[40:43], v[148:151], v[192:195], v[40:43]
	v_mfma_f32_16x16x32_bf16 v[40:43], v[152:155], v[196:199], v[40:43]
	v_mfma_f32_16x16x32_bf16 v[36:39], v[172:175], v[192:195], v[36:39]
	v_mfma_f32_16x16x32_bf16 v[36:39], v[180:183], v[196:199], v[36:39]
	v_mfma_f32_16x16x32_bf16 v[24:27], v[148:151], v[206:209], v[24:27]
	v_mfma_f32_16x16x32_bf16 v[24:27], v[152:155], v[210:213], v[24:27]
	v_mfma_f32_16x16x32_bf16 v[20:23], v[172:175], v[206:209], v[20:23]
	v_mfma_f32_16x16x32_bf16 v[20:23], v[180:183], v[210:213], v[20:23]
	v_mfma_f32_16x16x32_bf16 v[8:11], v[148:151], v[214:217], v[8:11]
	v_mfma_f32_16x16x32_bf16 v[8:11], v[152:155], v[248:251], v[8:11]
	v_mfma_f32_16x16x32_bf16 v[4:7], v[172:175], v[214:217], v[4:7]
	v_mfma_f32_16x16x32_bf16 v[4:7], v[180:183], v[248:251], v[4:7]
	s_setprio 0
	s_barrier
	s_add_i32 s66, s66, 2
	s_add_u32 s28, s28, 0x100
	s_addc_u32 s29, s29, 0
	s_add_u32 s64, s64, 0x100
	s_addc_u32 s65, s65, 0
	s_cmp_gt_u32 s66, 13
	s_cbranch_scc0 .LBB0_184
	s_and_b64 vcc, exec, s[52:53]
	s_cbranch_vccz .LBB0_187
	s_barrier

.LBB0_800:
	s_add_u32 s64, s62, 0x100
	s_addc_u32 s65, s63, 0
	s_add_i32 s72, 0, 0x10000
	s_cmp_eq_u32 s96, 12
	s_cselect_b32 s67, s57, s65
	s_cselect_b32 s66, s92, s64
	v_add_u32_e32 v145, s72, v142
	s_cselect_b32 s25, s55, s95
	s_cselect_b32 s24, s93, s94
	s_add_i32 s73, 0, 0x14000
	ds_read_b128 v[138:141], v145
	ds_read_b128 v[146:149], v145 offset:1024
	ds_read_b128 v[150:153], v145 offset:2048
	ds_read_b128 v[154:157], v145 offset:3072
	v_add_u32_e32 v145, s73, v142
	ds_read_b128 v[158:161], v145
	ds_read_b128 v[162:165], v145 offset:1024
	ds_read_b128 v[166:169], v145 offset:2048
	ds_read_b128 v[170:173], v145 offset:3072
	v_lshl_add_u64 v[174:175], s[62:63], 0, v[134:135]
	s_add_i32 m0, s84, 0xc000
	ds_read_b128 v[180:183], v144
	ds_read_b128 v[184:187], v144 offset:1024
	ds_read_b128 v[188:191], v144 offset:2048
	ds_read_b128 v[192:195], v144 offset:3072
	ds_read_b128 v[196:199], v144 offset:4096
	ds_read_b128 v[206:209], v144 offset:5120
	ds_read_b128 v[210:213], v144 offset:6144
	ds_read_b128 v[214:217], v144 offset:7168
	global_load_lds_dwordx4 v[174:175], off
	v_lshl_add_u64 v[174:175], s[62:63], 0, v[136:137]
	s_add_i32 m0, s84, 0xe000
	s_nop 0
	global_load_lds_dwordx4 v[174:175], off
	s_waitcnt vmcnt(8)
	s_waitcnt lgkmcnt(0)
	s_barrier
	s_setprio 1
	s_waitcnt lgkmcnt(0)
	v_mfma_f32_16x16x32_bf16 v[128:131], v[138:141], v[180:183], v[128:131]
	v_mfma_f32_16x16x32_bf16 v[128:131], v[146:149], v[184:187], v[128:131]
	v_mfma_f32_16x16x32_bf16 v[124:127], v[150:153], v[180:183], v[124:127]
	v_mfma_f32_16x16x32_bf16 v[124:127], v[154:157], v[184:187], v[124:127]
	v_mfma_f32_16x16x32_bf16 v[112:115], v[138:141], v[188:191], v[112:115]
	v_mfma_f32_16x16x32_bf16 v[112:115], v[146:149], v[192:195], v[112:115]
	v_mfma_f32_16x16x32_bf16 v[108:111], v[150:153], v[188:191], v[108:111]
	v_mfma_f32_16x16x32_bf16 v[108:111], v[154:157], v[192:195], v[108:111]
	v_mfma_f32_16x16x32_bf16 v[96:99], v[138:141], v[196:199], v[96:99]
	v_mfma_f32_16x16x32_bf16 v[96:99], v[146:149], v[206:209], v[96:99]
	v_mfma_f32_16x16x32_bf16 v[92:95], v[150:153], v[196:199], v[92:95]
	v_mfma_f32_16x16x32_bf16 v[92:95], v[154:157], v[206:209], v[92:95]
	v_mfma_f32_16x16x32_bf16 v[80:83], v[138:141], v[210:213], v[80:83]
	v_mfma_f32_16x16x32_bf16 v[80:83], v[146:149], v[214:217], v[80:83]
	v_mfma_f32_16x16x32_bf16 v[76:79], v[150:153], v[210:213], v[76:79]
	v_mfma_f32_16x16x32_bf16 v[76:79], v[154:157], v[214:217], v[76:79]
	s_setprio 0
	s_setprio 1
	v_mfma_f32_16x16x32_bf16 v[120:123], v[158:161], v[180:183], v[120:123]
	v_mfma_f32_16x16x32_bf16 v[120:123], v[162:165], v[184:187], v[120:123]
	v_mfma_f32_16x16x32_bf16 v[116:119], v[166:169], v[180:183], v[116:119]
	v_mfma_f32_16x16x32_bf16 v[116:119], v[170:173], v[184:187], v[116:119]
	v_mfma_f32_16x16x32_bf16 v[104:107], v[158:161], v[188:191], v[104:107]
	v_mfma_f32_16x16x32_bf16 v[104:107], v[162:165], v[192:195], v[104:107]
	v_mfma_f32_16x16x32_bf16 v[100:103], v[166:169], v[188:191], v[100:103]
	v_mfma_f32_16x16x32_bf16 v[100:103], v[170:173], v[192:195], v[100:103]
	v_mfma_f32_16x16x32_bf16 v[88:91], v[158:161], v[196:199], v[88:91]
	v_mfma_f32_16x16x32_bf16 v[88:91], v[162:165], v[206:209], v[88:91]
	v_mfma_f32_16x16x32_bf16 v[84:87], v[166:169], v[196:199], v[84:87]
	v_mfma_f32_16x16x32_bf16 v[84:87], v[170:173], v[206:209], v[84:87]
	v_mfma_f32_16x16x32_bf16 v[72:75], v[158:161], v[210:213], v[72:75]
	v_mfma_f32_16x16x32_bf16 v[72:75], v[162:165], v[214:217], v[72:75]
	v_mfma_f32_16x16x32_bf16 v[68:71], v[166:169], v[210:213], v[68:71]
	v_mfma_f32_16x16x32_bf16 v[68:71], v[170:173], v[214:217], v[68:71]
	s_setprio 0
	s_barrier
	s_add_i32 s62, s72, s71
	v_lshl_add_u64 v[174:175], s[24:25], 0, v[132:133]
	s_mov_b32 m0, s62
	ds_read_b128 v[180:183], v144 offset:16384
	ds_read_b128 v[184:187], v144 offset:17408
	ds_read_b128 v[188:191], v144 offset:18432
	ds_read_b128 v[192:195], v144 offset:19456
	ds_read_b128 v[196:199], v144 offset:20480
	ds_read_b128 v[206:209], v144 offset:21504
	ds_read_b128 v[210:213], v144 offset:22528
	ds_read_b128 v[214:217], v144 offset:23552
	global_load_lds_dwordx4 v[174:175], off
	s_add_i32 m0, s62, 0x2000
	s_add_u32 s62, s24, 0x40000
	v_lshl_add_u64 v[218:219], s[24:25], 0, v[0:1]
	s_addc_u32 s63, s25, 0
	s_add_i32 s72, s73, s71
	global_load_lds_dwordx4 v[218:219], off
	v_lshl_add_u64 v[220:221], s[62:63], 0, v[132:133]
	s_mov_b32 m0, s72
	v_lshl_add_u64 v[222:223], s[66:67], 0, v[0:1]
	global_load_lds_dwordx4 v[220:221], off
	v_lshl_add_u64 v[220:221], s[62:63], 0, v[0:1]
	s_add_i32 m0, s72, 0x2000
	s_nop 0
	global_load_lds_dwordx4 v[220:221], off
	v_lshl_add_u64 v[220:221], s[66:67], 0, v[132:133]
	s_mov_b32 m0, s84
	s_nop 0
	global_load_lds_dwordx4 v[220:221], off
	s_mov_b32 m0, s85
	s_nop 0
	global_load_lds_dwordx4 v[222:223], off
	s_waitcnt vmcnt(8)
	s_waitcnt lgkmcnt(0)
	s_barrier
	s_setprio 1
	s_waitcnt lgkmcnt(0)
	v_mfma_f32_16x16x32_bf16 v[64:67], v[138:141], v[180:183], v[64:67]
	v_mfma_f32_16x16x32_bf16 v[64:67], v[146:149], v[184:187], v[64:67]
	v_mfma_f32_16x16x32_bf16 v[60:63], v[150:153], v[180:183], v[60:63]
	v_mfma_f32_16x16x32_bf16 v[60:63], v[154:157], v[184:187], v[60:63]
	v_mfma_f32_16x16x32_bf16 v[48:51], v[138:141], v[188:191], v[48:51]
	v_mfma_f32_16x16x32_bf16 v[48:51], v[146:149], v[192:195], v[48:51]
	v_mfma_f32_16x16x32_bf16 v[44:47], v[150:153], v[188:191], v[44:47]
	v_mfma_f32_16x16x32_bf16 v[44:47], v[154:157], v[192:195], v[44:47]
	v_mfma_f32_16x16x32_bf16 v[32:35], v[138:141], v[196:199], v[32:35]
	v_mfma_f32_16x16x32_bf16 v[32:35], v[146:149], v[206:209], v[32:35]
	v_mfma_f32_16x16x32_bf16 v[28:31], v[150:153], v[196:199], v[28:31]
	v_mfma_f32_16x16x32_bf16 v[28:31], v[154:157], v[206:209], v[28:31]
	v_mfma_f32_16x16x32_bf16 v[16:19], v[138:141], v[210:213], v[16:19]
	v_mfma_f32_16x16x32_bf16 v[16:19], v[146:149], v[214:217], v[16:19]
	v_mfma_f32_16x16x32_bf16 v[12:15], v[150:153], v[210:213], v[12:15]
	v_mfma_f32_16x16x32_bf16 v[12:15], v[154:157], v[214:217], v[12:15]
	s_setprio 0
	s_setprio 1
	v_mfma_f32_16x16x32_bf16 v[56:59], v[158:161], v[180:183], v[56:59]
	v_mfma_f32_16x16x32_bf16 v[56:59], v[162:165], v[184:187], v[56:59]
	v_mfma_f32_16x16x32_bf16 v[52:55], v[166:169], v[180:183], v[52:55]
	v_mfma_f32_16x16x32_bf16 v[52:55], v[170:173], v[184:187], v[52:55]
	v_mfma_f32_16x16x32_bf16 v[40:43], v[158:161], v[188:191], v[40:43]
	v_mfma_f32_16x16x32_bf16 v[40:43], v[162:165], v[192:195], v[40:43]
	v_mfma_f32_16x16x32_bf16 v[36:39], v[166:169], v[188:191], v[36:39]
	v_mfma_f32_16x16x32_bf16 v[36:39], v[170:173], v[192:195], v[36:39]
	v_mfma_f32_16x16x32_bf16 v[24:27], v[158:161], v[196:199], v[24:27]
	v_mfma_f32_16x16x32_bf16 v[24:27], v[162:165], v[206:209], v[24:27]
	v_mfma_f32_16x16x32_bf16 v[20:23], v[166:169], v[196:199], v[20:23]
	v_mfma_f32_16x16x32_bf16 v[20:23], v[170:173], v[206:209], v[20:23]
	v_mfma_f32_16x16x32_bf16 v[8:11], v[158:161], v[210:213], v[8:11]
	v_mfma_f32_16x16x32_bf16 v[8:11], v[162:165], v[214:217], v[8:11]
	v_mfma_f32_16x16x32_bf16 v[4:7], v[166:169], v[210:213], v[4:7]
	v_mfma_f32_16x16x32_bf16 v[4:7], v[170:173], v[214:217], v[4:7]
	s_setprio 0
	s_barrier
	s_add_i32 s72, 0, 0x18000
	v_add_u32_e32 v145, s72, v142
	s_add_i32 s73, 0, 0x1c000
	ds_read_b128 v[138:141], v145
	ds_read_b128 v[146:149], v145 offset:1024
	ds_read_b128 v[150:153], v145 offset:2048
	ds_read_b128 v[154:157], v145 offset:3072
	v_add_u32_e32 v145, s73, v142
	ds_read_b128 v[158:161], v145
	ds_read_b128 v[162:165], v145 offset:1024
	ds_read_b128 v[166:169], v145 offset:2048
	ds_read_b128 v[170:173], v145 offset:3072
	s_add_u32 s62, s66, 0x40000
	s_addc_u32 s63, s67, 0
	s_mov_b32 m0, s86
	v_lshl_add_u64 v[224:225], s[62:63], 0, v[132:133]
	ds_read_b128 v[180:183], v144 offset:32768
	ds_read_b128 v[184:187], v144 offset:33792
	ds_read_b128 v[188:191], v144 offset:34816
	ds_read_b128 v[192:195], v144 offset:35840
	ds_read_b128 v[196:199], v144 offset:36864
	ds_read_b128 v[206:209], v144 offset:37888
	ds_read_b128 v[210:213], v144 offset:38912
	ds_read_b128 v[214:217], v144 offset:39936
	global_load_lds_dwordx4 v[224:225], off
	v_lshl_add_u64 v[224:225], s[62:63], 0, v[0:1]
	s_mov_b32 m0, s87
	s_nop 0
	global_load_lds_dwordx4 v[224:225], off
	s_waitcnt vmcnt(8)
	s_waitcnt lgkmcnt(0)
	s_barrier
	s_setprio 1
	s_waitcnt lgkmcnt(0)
	v_mfma_f32_16x16x32_bf16 v[128:131], v[138:141], v[180:183], v[128:131]
	v_mfma_f32_16x16x32_bf16 v[128:131], v[146:149], v[184:187], v[128:131]
	v_mfma_f32_16x16x32_bf16 v[124:127], v[150:153], v[180:183], v[124:127]
	v_mfma_f32_16x16x32_bf16 v[124:127], v[154:157], v[184:187], v[124:127]
	v_mfma_f32_16x16x32_bf16 v[112:115], v[138:141], v[188:191], v[112:115]
	v_mfma_f32_16x16x32_bf16 v[112:115], v[146:149], v[192:195], v[112:115]
	v_mfma_f32_16x16x32_bf16 v[108:111], v[150:153], v[188:191], v[108:111]
	v_mfma_f32_16x16x32_bf16 v[108:111], v[154:157], v[192:195], v[108:111]
	v_mfma_f32_16x16x32_bf16 v[96:99], v[138:141], v[196:199], v[96:99]
	v_mfma_f32_16x16x32_bf16 v[96:99], v[146:149], v[206:209], v[96:99]
	v_mfma_f32_16x16x32_bf16 v[92:95], v[150:153], v[196:199], v[92:95]
	v_mfma_f32_16x16x32_bf16 v[92:95], v[154:157], v[206:209], v[92:95]
	v_mfma_f32_16x16x32_bf16 v[80:83], v[138:141], v[210:213], v[80:83]
	v_mfma_f32_16x16x32_bf16 v[80:83], v[146:149], v[214:217], v[80:83]
	v_mfma_f32_16x16x32_bf16 v[76:79], v[150:153], v[210:213], v[76:79]
	v_mfma_f32_16x16x32_bf16 v[76:79], v[154:157], v[214:217], v[76:79]
	s_setprio 0
	s_setprio 1
	v_mfma_f32_16x16x32_bf16 v[120:123], v[158:161], v[180:183], v[120:123]
	v_mfma_f32_16x16x32_bf16 v[120:123], v[162:165], v[184:187], v[120:123]
	v_mfma_f32_16x16x32_bf16 v[116:119], v[166:169], v[180:183], v[116:119]
	v_mfma_f32_16x16x32_bf16 v[116:119], v[170:173], v[184:187], v[116:119]
	v_mfma_f32_16x16x32_bf16 v[104:107], v[158:161], v[188:191], v[104:107]
	v_mfma_f32_16x16x32_bf16 v[104:107], v[162:165], v[192:195], v[104:107]
	v_mfma_f32_16x16x32_bf16 v[100:103], v[166:169], v[188:191], v[100:103]
	v_mfma_f32_16x16x32_bf16 v[100:103], v[170:173], v[192:195], v[100:103]
	v_mfma_f32_16x16x32_bf16 v[88:91], v[158:161], v[196:199], v[88:91]
	v_mfma_f32_16x16x32_bf16 v[88:91], v[162:165], v[206:209], v[88:91]
	v_mfma_f32_16x16x32_bf16 v[84:87], v[166:169], v[196:199], v[84:87]
	v_mfma_f32_16x16x32_bf16 v[84:87], v[170:173], v[206:209], v[84:87]
	v_mfma_f32_16x16x32_bf16 v[72:75], v[158:161], v[210:213], v[72:75]
	v_mfma_f32_16x16x32_bf16 v[72:75], v[162:165], v[214:217], v[72:75]
	v_mfma_f32_16x16x32_bf16 v[68:71], v[166:169], v[210:213], v[68:71]
	v_mfma_f32_16x16x32_bf16 v[68:71], v[170:173], v[214:217], v[68:71]
	s_setprio 0
	s_barrier
	s_add_i32 s62, s72, s71
	v_lshl_add_u64 v[174:175], v[174:175], 0, s[30:31]
	s_mov_b32 m0, s62
	ds_read_b128 v[180:183], v144 offset:49152
	ds_read_b128 v[184:187], v144 offset:50176
	ds_read_b128 v[188:191], v144 offset:51200
	ds_read_b128 v[192:195], v144 offset:52224
	ds_read_b128 v[196:199], v144 offset:53248
	ds_read_b128 v[206:209], v144 offset:54272
	ds_read_b128 v[210:213], v144 offset:55296
	ds_read_b128 v[214:217], v144 offset:56320
	global_load_lds_dwordx4 v[174:175], off
	s_add_i32 m0, s62, 0x2000
	s_add_u32 s24, s24, 0x40080
	v_lshl_add_u64 v[174:175], v[218:219], 0, s[30:31]
	s_addc_u32 s25, s25, 0
	s_add_i32 s62, s73, s71
	global_load_lds_dwordx4 v[174:175], off
	v_lshl_add_u64 v[174:175], s[24:25], 0, v[132:133]
	s_mov_b32 m0, s62
	s_nop 0
	global_load_lds_dwordx4 v[174:175], off
	v_lshl_add_u64 v[174:175], s[24:25], 0, v[0:1]
	s_add_i32 m0, s62, 0x2000
	s_nop 0
	global_load_lds_dwordx4 v[174:175], off
	v_lshl_add_u64 v[174:175], v[220:221], 0, s[30:31]
	s_mov_b32 m0, s26
	s_nop 0
	global_load_lds_dwordx4 v[174:175], off
	v_lshl_add_u64 v[174:175], v[222:223], 0, s[30:31]
	s_mov_b32 m0, s88
	s_nop 0
	global_load_lds_dwordx4 v[174:175], off
	s_waitcnt vmcnt(8)
	s_waitcnt lgkmcnt(0)
	s_barrier
	s_setprio 1
	s_waitcnt lgkmcnt(0)
	v_mfma_f32_16x16x32_bf16 v[64:67], v[138:141], v[180:183], v[64:67]
	v_mfma_f32_16x16x32_bf16 v[64:67], v[146:149], v[184:187], v[64:67]
	v_mfma_f32_16x16x32_bf16 v[60:63], v[150:153], v[180:183], v[60:63]
	v_mfma_f32_16x16x32_bf16 v[60:63], v[154:157], v[184:187], v[60:63]
	v_mfma_f32_16x16x32_bf16 v[48:51], v[138:141], v[188:191], v[48:51]
	v_mfma_f32_16x16x32_bf16 v[48:51], v[146:149], v[192:195], v[48:51]
	v_mfma_f32_16x16x32_bf16 v[44:47], v[150:153], v[188:191], v[44:47]
	v_mfma_f32_16x16x32_bf16 v[44:47], v[154:157], v[192:195], v[44:47]
	v_mfma_f32_16x16x32_bf16 v[32:35], v[138:141], v[196:199], v[32:35]
	v_mfma_f32_16x16x32_bf16 v[32:35], v[146:149], v[206:209], v[32:35]
	v_mfma_f32_16x16x32_bf16 v[28:31], v[150:153], v[196:199], v[28:31]
	v_mfma_f32_16x16x32_bf16 v[28:31], v[154:157], v[206:209], v[28:31]
	v_mfma_f32_16x16x32_bf16 v[16:19], v[138:141], v[210:213], v[16:19]
	v_mfma_f32_16x16x32_bf16 v[16:19], v[146:149], v[214:217], v[16:19]
	v_mfma_f32_16x16x32_bf16 v[12:15], v[150:153], v[210:213], v[12:15]
	v_mfma_f32_16x16x32_bf16 v[12:15], v[154:157], v[214:217], v[12:15]
	s_setprio 0
	s_setprio 1
	v_mfma_f32_16x16x32_bf16 v[56:59], v[158:161], v[180:183], v[56:59]
	v_mfma_f32_16x16x32_bf16 v[56:59], v[162:165], v[184:187], v[56:59]
	v_mfma_f32_16x16x32_bf16 v[52:55], v[166:169], v[180:183], v[52:55]
	v_mfma_f32_16x16x32_bf16 v[52:55], v[170:173], v[184:187], v[52:55]
	v_mfma_f32_16x16x32_bf16 v[40:43], v[158:161], v[188:191], v[40:43]
	v_mfma_f32_16x16x32_bf16 v[40:43], v[162:165], v[192:195], v[40:43]
	v_mfma_f32_16x16x32_bf16 v[36:39], v[166:169], v[188:191], v[36:39]
	v_mfma_f32_16x16x32_bf16 v[36:39], v[170:173], v[192:195], v[36:39]
	v_mfma_f32_16x16x32_bf16 v[24:27], v[158:161], v[196:199], v[24:27]
	v_mfma_f32_16x16x32_bf16 v[24:27], v[162:165], v[206:209], v[24:27]
	v_mfma_f32_16x16x32_bf16 v[20:23], v[166:169], v[196:199], v[20:23]
	v_mfma_f32_16x16x32_bf16 v[20:23], v[170:173], v[206:209], v[20:23]
	v_mfma_f32_16x16x32_bf16 v[8:11], v[158:161], v[210:213], v[8:11]
	v_mfma_f32_16x16x32_bf16 v[8:11], v[162:165], v[214:217], v[8:11]
	v_mfma_f32_16x16x32_bf16 v[4:7], v[166:169], v[210:213], v[4:7]
	v_mfma_f32_16x16x32_bf16 v[4:7], v[170:173], v[214:217], v[4:7]
	s_setprio 0
	s_barrier
	s_add_i32 s96, s96, 2
	s_add_u32 s94, s94, 0x100
	s_addc_u32 s95, s95, 0
	s_cmp_gt_u32 s96, 13
	s_mov_b64 s[62:63], s[64:65]
	s_cbranch_scc0 .LBB0_800
	s_and_b64 vcc, exec, s[52:53]
	s_cbranch_vccz .LBB0_803
	s_barrier

.LBB0_889:
	s_add_u32 s24, s28, 0xfffc0080
	s_addc_u32 s25, s29, -1
	s_add_i32 s72, 0, 0x10000
	s_cmp_eq_u32 s88, 12
	s_cselect_b32 s59, s53, s25
	s_cselect_b32 s58, s84, s24
	v_add_u32_e32 v149, s72, v146
	s_cselect_b32 s25, s51, s87
	s_cselect_b32 s24, s85, s86
	s_add_i32 s89, 0, 0x14000
	ds_read_b128 v[138:141], v149
	ds_read_b128 v[142:145], v149 offset:1024
	ds_read_b128 v[150:153], v149 offset:2048
	ds_read_b128 v[154:157], v149 offset:3072
	v_add_u32_e32 v149, s89, v146
	ds_read_b128 v[158:161], v149
	ds_read_b128 v[162:165], v149 offset:1024
	ds_read_b128 v[166:169], v149 offset:2048
	ds_read_b128 v[170:173], v149 offset:3072
	v_lshl_add_u64 v[174:175], s[28:29], 0, v[134:135]
	s_add_i32 m0, s64, 0xc000
	ds_read_b128 v[180:183], v148
	ds_read_b128 v[184:187], v148 offset:1024
	ds_read_b128 v[188:191], v148 offset:2048
	ds_read_b128 v[192:195], v148 offset:3072
	ds_read_b128 v[196:199], v148 offset:4096
	ds_read_b128 v[206:209], v148 offset:5120
	ds_read_b128 v[210:213], v148 offset:6144
	ds_read_b128 v[214:217], v148 offset:7168
	global_load_lds_dwordx4 v[174:175], off
	v_lshl_add_u64 v[174:175], s[28:29], 0, v[136:137]
	s_add_i32 m0, s64, 0xe000
	s_nop 0
	global_load_lds_dwordx4 v[174:175], off
	s_waitcnt vmcnt(8)
	s_waitcnt lgkmcnt(0)
	s_barrier
	s_setprio 1
	s_waitcnt lgkmcnt(0)
	v_mfma_f32_16x16x32_bf16 v[128:131], v[138:141], v[180:183], v[128:131]
	v_mfma_f32_16x16x32_bf16 v[128:131], v[142:145], v[184:187], v[128:131]
	v_mfma_f32_16x16x32_bf16 v[124:127], v[150:153], v[180:183], v[124:127]
	v_mfma_f32_16x16x32_bf16 v[124:127], v[154:157], v[184:187], v[124:127]
	v_mfma_f32_16x16x32_bf16 v[112:115], v[138:141], v[188:191], v[112:115]
	v_mfma_f32_16x16x32_bf16 v[112:115], v[142:145], v[192:195], v[112:115]
	v_mfma_f32_16x16x32_bf16 v[108:111], v[150:153], v[188:191], v[108:111]
	v_mfma_f32_16x16x32_bf16 v[108:111], v[154:157], v[192:195], v[108:111]
	v_mfma_f32_16x16x32_bf16 v[96:99], v[138:141], v[196:199], v[96:99]
	v_mfma_f32_16x16x32_bf16 v[96:99], v[142:145], v[206:209], v[96:99]
	v_mfma_f32_16x16x32_bf16 v[92:95], v[150:153], v[196:199], v[92:95]
	v_mfma_f32_16x16x32_bf16 v[92:95], v[154:157], v[206:209], v[92:95]
	v_mfma_f32_16x16x32_bf16 v[80:83], v[138:141], v[210:213], v[80:83]
	v_mfma_f32_16x16x32_bf16 v[80:83], v[142:145], v[214:217], v[80:83]
	v_mfma_f32_16x16x32_bf16 v[76:79], v[150:153], v[210:213], v[76:79]
	v_mfma_f32_16x16x32_bf16 v[76:79], v[154:157], v[214:217], v[76:79]
	s_setprio 0
	s_setprio 1
	v_mfma_f32_16x16x32_bf16 v[120:123], v[158:161], v[180:183], v[120:123]
	v_mfma_f32_16x16x32_bf16 v[120:123], v[162:165], v[184:187], v[120:123]
	v_mfma_f32_16x16x32_bf16 v[116:119], v[166:169], v[180:183], v[116:119]
	v_mfma_f32_16x16x32_bf16 v[116:119], v[170:173], v[184:187], v[116:119]
	v_mfma_f32_16x16x32_bf16 v[104:107], v[158:161], v[188:191], v[104:107]
	v_mfma_f32_16x16x32_bf16 v[104:107], v[162:165], v[192:195], v[104:107]
	v_mfma_f32_16x16x32_bf16 v[100:103], v[166:169], v[188:191], v[100:103]
	v_mfma_f32_16x16x32_bf16 v[100:103], v[170:173], v[192:195], v[100:103]
	v_mfma_f32_16x16x32_bf16 v[88:91], v[158:161], v[196:199], v[88:91]
	v_mfma_f32_16x16x32_bf16 v[88:91], v[162:165], v[206:209], v[88:91]
	v_mfma_f32_16x16x32_bf16 v[84:87], v[166:169], v[196:199], v[84:87]
	v_mfma_f32_16x16x32_bf16 v[84:87], v[170:173], v[206:209], v[84:87]
	v_mfma_f32_16x16x32_bf16 v[72:75], v[158:161], v[210:213], v[72:75]
	v_mfma_f32_16x16x32_bf16 v[72:75], v[162:165], v[214:217], v[72:75]
	v_mfma_f32_16x16x32_bf16 v[68:71], v[166:169], v[210:213], v[68:71]
	v_mfma_f32_16x16x32_bf16 v[68:71], v[170:173], v[214:217], v[68:71]
	s_setprio 0
	s_barrier
	s_add_i32 s72, s72, s63
	v_lshl_add_u64 v[174:175], s[24:25], 0, v[132:133]
	s_mov_b32 m0, s72
	ds_read_b128 v[180:183], v148 offset:16384
	ds_read_b128 v[184:187], v148 offset:17408
	ds_read_b128 v[188:191], v148 offset:18432
	ds_read_b128 v[192:195], v148 offset:19456
	ds_read_b128 v[196:199], v148 offset:20480
	ds_read_b128 v[206:209], v148 offset:21504
	ds_read_b128 v[210:213], v148 offset:22528
	ds_read_b128 v[214:217], v148 offset:23552
	global_load_lds_dwordx4 v[174:175], off
	s_add_i32 m0, s72, 0x2000
	s_add_u32 s72, s24, 0x40000
	v_lshl_add_u64 v[218:219], s[24:25], 0, v[0:1]
	s_addc_u32 s73, s25, 0
	s_add_i32 s89, s89, s63
	global_load_lds_dwordx4 v[218:219], off
	v_lshl_add_u64 v[220:221], s[72:73], 0, v[132:133]
	s_mov_b32 m0, s89
	v_lshl_add_u64 v[222:223], s[58:59], 0, v[0:1]
	global_load_lds_dwordx4 v[220:221], off
	v_lshl_add_u64 v[220:221], s[72:73], 0, v[0:1]
	s_add_i32 m0, s89, 0x2000
	s_nop 0
	global_load_lds_dwordx4 v[220:221], off
	v_lshl_add_u64 v[220:221], s[58:59], 0, v[132:133]
	s_mov_b32 m0, s64
	s_nop 0
	global_load_lds_dwordx4 v[220:221], off
	s_mov_b32 m0, s65
	s_nop 0
	global_load_lds_dwordx4 v[222:223], off
	s_waitcnt vmcnt(8)
	s_waitcnt lgkmcnt(0)
	s_barrier
	s_setprio 1
	s_waitcnt lgkmcnt(0)
	v_mfma_f32_16x16x32_bf16 v[64:67], v[138:141], v[180:183], v[64:67]
	v_mfma_f32_16x16x32_bf16 v[64:67], v[142:145], v[184:187], v[64:67]
	v_mfma_f32_16x16x32_bf16 v[60:63], v[150:153], v[180:183], v[60:63]
	v_mfma_f32_16x16x32_bf16 v[60:63], v[154:157], v[184:187], v[60:63]
	v_mfma_f32_16x16x32_bf16 v[48:51], v[138:141], v[188:191], v[48:51]
	v_mfma_f32_16x16x32_bf16 v[48:51], v[142:145], v[192:195], v[48:51]
	v_mfma_f32_16x16x32_bf16 v[44:47], v[150:153], v[188:191], v[44:47]
	v_mfma_f32_16x16x32_bf16 v[44:47], v[154:157], v[192:195], v[44:47]
	v_mfma_f32_16x16x32_bf16 v[32:35], v[138:141], v[196:199], v[32:35]
	v_mfma_f32_16x16x32_bf16 v[32:35], v[142:145], v[206:209], v[32:35]
	v_mfma_f32_16x16x32_bf16 v[28:31], v[150:153], v[196:199], v[28:31]
	v_mfma_f32_16x16x32_bf16 v[28:31], v[154:157], v[206:209], v[28:31]
	v_mfma_f32_16x16x32_bf16 v[16:19], v[138:141], v[210:213], v[16:19]
	v_mfma_f32_16x16x32_bf16 v[16:19], v[142:145], v[214:217], v[16:19]
	v_mfma_f32_16x16x32_bf16 v[12:15], v[150:153], v[210:213], v[12:15]
	v_mfma_f32_16x16x32_bf16 v[12:15], v[154:157], v[214:217], v[12:15]
	s_setprio 0
	s_setprio 1
	v_mfma_f32_16x16x32_bf16 v[56:59], v[158:161], v[180:183], v[56:59]
	v_mfma_f32_16x16x32_bf16 v[56:59], v[162:165], v[184:187], v[56:59]
	v_mfma_f32_16x16x32_bf16 v[52:55], v[166:169], v[180:183], v[52:55]
	v_mfma_f32_16x16x32_bf16 v[52:55], v[170:173], v[184:187], v[52:55]
	v_mfma_f32_16x16x32_bf16 v[40:43], v[158:161], v[188:191], v[40:43]
	v_mfma_f32_16x16x32_bf16 v[40:43], v[162:165], v[192:195], v[40:43]
	v_mfma_f32_16x16x32_bf16 v[36:39], v[166:169], v[188:191], v[36:39]
	v_mfma_f32_16x16x32_bf16 v[36:39], v[170:173], v[192:195], v[36:39]
	v_mfma_f32_16x16x32_bf16 v[24:27], v[158:161], v[196:199], v[24:27]
	v_mfma_f32_16x16x32_bf16 v[24:27], v[162:165], v[206:209], v[24:27]
	v_mfma_f32_16x16x32_bf16 v[20:23], v[166:169], v[196:199], v[20:23]
	v_mfma_f32_16x16x32_bf16 v[20:23], v[170:173], v[206:209], v[20:23]
	v_mfma_f32_16x16x32_bf16 v[8:11], v[158:161], v[210:213], v[8:11]
	v_mfma_f32_16x16x32_bf16 v[8:11], v[162:165], v[214:217], v[8:11]
	v_mfma_f32_16x16x32_bf16 v[4:7], v[166:169], v[210:213], v[4:7]
	v_mfma_f32_16x16x32_bf16 v[4:7], v[170:173], v[214:217], v[4:7]
	s_setprio 0
	s_barrier
	s_add_i32 s72, 0, 0x18000
	v_add_u32_e32 v149, s72, v146
	s_add_i32 s73, 0, 0x1c000
	ds_read_b128 v[138:141], v149
	ds_read_b128 v[142:145], v149 offset:1024
	ds_read_b128 v[150:153], v149 offset:2048
	ds_read_b128 v[154:157], v149 offset:3072
	v_add_u32_e32 v149, s73, v146
	ds_read_b128 v[158:161], v149
	ds_read_b128 v[162:165], v149 offset:1024
	ds_read_b128 v[166:169], v149 offset:2048
	ds_read_b128 v[170:173], v149 offset:3072
	s_add_u32 s58, s58, 0x40000
	s_addc_u32 s59, s59, 0
	s_mov_b32 m0, s66
	v_lshl_add_u64 v[224:225], s[58:59], 0, v[132:133]
	ds_read_b128 v[180:183], v148 offset:32768
	ds_read_b128 v[184:187], v148 offset:33792
	ds_read_b128 v[188:191], v148 offset:34816
	ds_read_b128 v[192:195], v148 offset:35840
	ds_read_b128 v[196:199], v148 offset:36864
	ds_read_b128 v[206:209], v148 offset:37888
	ds_read_b128 v[210:213], v148 offset:38912
	ds_read_b128 v[214:217], v148 offset:39936
	global_load_lds_dwordx4 v[224:225], off
	v_lshl_add_u64 v[224:225], s[58:59], 0, v[0:1]
	s_mov_b32 m0, s67
	s_nop 0
	global_load_lds_dwordx4 v[224:225], off
	s_waitcnt vmcnt(8)
	s_waitcnt lgkmcnt(0)
	s_barrier
	s_setprio 1
	s_waitcnt lgkmcnt(0)
	v_mfma_f32_16x16x32_bf16 v[128:131], v[138:141], v[180:183], v[128:131]
	v_mfma_f32_16x16x32_bf16 v[128:131], v[142:145], v[184:187], v[128:131]
	v_mfma_f32_16x16x32_bf16 v[124:127], v[150:153], v[180:183], v[124:127]
	v_mfma_f32_16x16x32_bf16 v[124:127], v[154:157], v[184:187], v[124:127]
	v_mfma_f32_16x16x32_bf16 v[112:115], v[138:141], v[188:191], v[112:115]
	v_mfma_f32_16x16x32_bf16 v[112:115], v[142:145], v[192:195], v[112:115]
	v_mfma_f32_16x16x32_bf16 v[108:111], v[150:153], v[188:191], v[108:111]
	v_mfma_f32_16x16x32_bf16 v[108:111], v[154:157], v[192:195], v[108:111]
	v_mfma_f32_16x16x32_bf16 v[96:99], v[138:141], v[196:199], v[96:99]
	v_mfma_f32_16x16x32_bf16 v[96:99], v[142:145], v[206:209], v[96:99]
	v_mfma_f32_16x16x32_bf16 v[92:95], v[150:153], v[196:199], v[92:95]
	v_mfma_f32_16x16x32_bf16 v[92:95], v[154:157], v[206:209], v[92:95]
	v_mfma_f32_16x16x32_bf16 v[80:83], v[138:141], v[210:213], v[80:83]
	v_mfma_f32_16x16x32_bf16 v[80:83], v[142:145], v[214:217], v[80:83]
	v_mfma_f32_16x16x32_bf16 v[76:79], v[150:153], v[210:213], v[76:79]
	v_mfma_f32_16x16x32_bf16 v[76:79], v[154:157], v[214:217], v[76:79]
	s_setprio 0
	s_setprio 1
	v_mfma_f32_16x16x32_bf16 v[120:123], v[158:161], v[180:183], v[120:123]
	v_mfma_f32_16x16x32_bf16 v[120:123], v[162:165], v[184:187], v[120:123]
	v_mfma_f32_16x16x32_bf16 v[116:119], v[166:169], v[180:183], v[116:119]
	v_mfma_f32_16x16x32_bf16 v[116:119], v[170:173], v[184:187], v[116:119]
	v_mfma_f32_16x16x32_bf16 v[104:107], v[158:161], v[188:191], v[104:107]
	v_mfma_f32_16x16x32_bf16 v[104:107], v[162:165], v[192:195], v[104:107]
	v_mfma_f32_16x16x32_bf16 v[100:103], v[166:169], v[188:191], v[100:103]
	v_mfma_f32_16x16x32_bf16 v[100:103], v[170:173], v[192:195], v[100:103]
	v_mfma_f32_16x16x32_bf16 v[88:91], v[158:161], v[196:199], v[88:91]
	v_mfma_f32_16x16x32_bf16 v[88:91], v[162:165], v[206:209], v[88:91]
	v_mfma_f32_16x16x32_bf16 v[84:87], v[166:169], v[196:199], v[84:87]
	v_mfma_f32_16x16x32_bf16 v[84:87], v[170:173], v[206:209], v[84:87]
	v_mfma_f32_16x16x32_bf16 v[72:75], v[158:161], v[210:213], v[72:75]
	v_mfma_f32_16x16x32_bf16 v[72:75], v[162:165], v[214:217], v[72:75]
	v_mfma_f32_16x16x32_bf16 v[68:71], v[166:169], v[210:213], v[68:71]
	v_mfma_f32_16x16x32_bf16 v[68:71], v[170:173], v[214:217], v[68:71]
	s_setprio 0
	s_barrier
	s_add_i32 s58, s72, s63
	v_lshl_add_u64 v[174:175], v[174:175], 0, s[30:31]
	s_mov_b32 m0, s58
	ds_read_b128 v[180:183], v148 offset:49152
	ds_read_b128 v[184:187], v148 offset:50176
	ds_read_b128 v[188:191], v148 offset:51200
	ds_read_b128 v[192:195], v148 offset:52224
	ds_read_b128 v[196:199], v148 offset:53248
	ds_read_b128 v[206:209], v148 offset:54272
	ds_read_b128 v[210:213], v148 offset:55296
	ds_read_b128 v[214:217], v148 offset:56320
	global_load_lds_dwordx4 v[174:175], off
	s_add_i32 m0, s58, 0x2000
	s_add_u32 s24, s24, 0x40080
	v_lshl_add_u64 v[174:175], v[218:219], 0, s[30:31]
	s_addc_u32 s25, s25, 0
	s_add_i32 s58, s73, s63
	global_load_lds_dwordx4 v[174:175], off
	v_lshl_add_u64 v[174:175], s[24:25], 0, v[132:133]
	s_mov_b32 m0, s58
	s_nop 0
	global_load_lds_dwordx4 v[174:175], off
	v_lshl_add_u64 v[174:175], s[24:25], 0, v[0:1]
	s_add_i32 m0, s58, 0x2000
	s_nop 0
	global_load_lds_dwordx4 v[174:175], off
	v_lshl_add_u64 v[174:175], v[220:221], 0, s[30:31]
	s_mov_b32 m0, s26
	s_nop 0
	global_load_lds_dwordx4 v[174:175], off
	v_lshl_add_u64 v[174:175], v[222:223], 0, s[30:31]
	s_mov_b32 m0, s68
	s_nop 0
	global_load_lds_dwordx4 v[174:175], off
	s_waitcnt vmcnt(8)
	s_waitcnt lgkmcnt(0)
	s_barrier
	s_setprio 1
	s_waitcnt lgkmcnt(0)
	v_mfma_f32_16x16x32_bf16 v[64:67], v[138:141], v[180:183], v[64:67]
	v_mfma_f32_16x16x32_bf16 v[64:67], v[142:145], v[184:187], v[64:67]
	v_mfma_f32_16x16x32_bf16 v[60:63], v[150:153], v[180:183], v[60:63]
	v_mfma_f32_16x16x32_bf16 v[60:63], v[154:157], v[184:187], v[60:63]
	v_mfma_f32_16x16x32_bf16 v[48:51], v[138:141], v[188:191], v[48:51]
	v_mfma_f32_16x16x32_bf16 v[48:51], v[142:145], v[192:195], v[48:51]
	v_mfma_f32_16x16x32_bf16 v[44:47], v[150:153], v[188:191], v[44:47]
	v_mfma_f32_16x16x32_bf16 v[44:47], v[154:157], v[192:195], v[44:47]
	v_mfma_f32_16x16x32_bf16 v[32:35], v[138:141], v[196:199], v[32:35]
	v_mfma_f32_16x16x32_bf16 v[32:35], v[142:145], v[206:209], v[32:35]
	v_mfma_f32_16x16x32_bf16 v[28:31], v[150:153], v[196:199], v[28:31]
	v_mfma_f32_16x16x32_bf16 v[28:31], v[154:157], v[206:209], v[28:31]
	v_mfma_f32_16x16x32_bf16 v[16:19], v[138:141], v[210:213], v[16:19]
	v_mfma_f32_16x16x32_bf16 v[16:19], v[142:145], v[214:217], v[16:19]
	v_mfma_f32_16x16x32_bf16 v[12:15], v[150:153], v[210:213], v[12:15]
	v_mfma_f32_16x16x32_bf16 v[12:15], v[154:157], v[214:217], v[12:15]
	s_setprio 0
	s_setprio 1
	v_mfma_f32_16x16x32_bf16 v[56:59], v[158:161], v[180:183], v[56:59]
	v_mfma_f32_16x16x32_bf16 v[56:59], v[162:165], v[184:187], v[56:59]
	v_mfma_f32_16x16x32_bf16 v[52:55], v[166:169], v[180:183], v[52:55]
	v_mfma_f32_16x16x32_bf16 v[52:55], v[170:173], v[184:187], v[52:55]
	v_mfma_f32_16x16x32_bf16 v[40:43], v[158:161], v[188:191], v[40:43]
	v_mfma_f32_16x16x32_bf16 v[40:43], v[162:165], v[192:195], v[40:43]
	v_mfma_f32_16x16x32_bf16 v[36:39], v[166:169], v[188:191], v[36:39]
	v_mfma_f32_16x16x32_bf16 v[36:39], v[170:173], v[192:195], v[36:39]
	v_mfma_f32_16x16x32_bf16 v[24:27], v[158:161], v[196:199], v[24:27]
	v_mfma_f32_16x16x32_bf16 v[24:27], v[162:165], v[206:209], v[24:27]
	v_mfma_f32_16x16x32_bf16 v[20:23], v[166:169], v[196:199], v[20:23]
	v_mfma_f32_16x16x32_bf16 v[20:23], v[170:173], v[206:209], v[20:23]
	v_mfma_f32_16x16x32_bf16 v[8:11], v[158:161], v[210:213], v[8:11]
	v_mfma_f32_16x16x32_bf16 v[8:11], v[162:165], v[214:217], v[8:11]
	v_mfma_f32_16x16x32_bf16 v[4:7], v[166:169], v[210:213], v[4:7]
	v_mfma_f32_16x16x32_bf16 v[4:7], v[170:173], v[214:217], v[4:7]
	s_setprio 0
	s_barrier
	s_add_i32 s88, s88, 2
	s_add_u32 s28, s28, 0x100
	s_addc_u32 s29, s29, 0
	s_add_u32 s86, s86, 0x100
	s_addc_u32 s87, s87, 0
	s_cmp_gt_u32 s88, 13
	s_cbranch_scc0 .LBB0_889
	s_and_b64 vcc, exec, s[48:49]
	s_cbranch_vccz .LBB0_892
	s_barrier

.LBB0_961:
	s_add_u32 s60, s28, 0x100
	s_addc_u32 s61, s29, 0
	s_add_i32 s72, 0, 0x10000
	s_cmp_eq_u32 s92, 60
	s_cselect_b32 s63, s55, s61
	s_cselect_b32 s62, s88, s60
	v_add_u32_e32 v149, s72, v146
	s_cselect_b32 s25, s53, s91
	s_cselect_b32 s24, s89, s90
	s_add_i32 s73, 0, 0x14000
	ds_read_b128 v[138:141], v149
	ds_read_b128 v[142:145], v149 offset:1024
	ds_read_b128 v[150:153], v149 offset:2048
	ds_read_b128 v[154:157], v149 offset:3072
	v_add_u32_e32 v149, s73, v146
	ds_read_b128 v[158:161], v149
	ds_read_b128 v[162:165], v149 offset:1024
	ds_read_b128 v[166:169], v149 offset:2048
	ds_read_b128 v[170:173], v149 offset:3072
	v_lshl_add_u64 v[174:175], s[28:29], 0, v[134:135]
	s_add_i32 m0, s67, 0xc000
	ds_read_b128 v[180:183], v148
	ds_read_b128 v[184:187], v148 offset:1024
	ds_read_b128 v[188:191], v148 offset:2048
	ds_read_b128 v[192:195], v148 offset:3072
	ds_read_b128 v[196:199], v148 offset:4096
	ds_read_b128 v[206:209], v148 offset:5120
	ds_read_b128 v[210:213], v148 offset:6144
	ds_read_b128 v[214:217], v148 offset:7168
	global_load_lds_dwordx4 v[174:175], off
	v_lshl_add_u64 v[174:175], s[28:29], 0, v[136:137]
	s_add_i32 m0, s67, 0xe000
	s_nop 0
	global_load_lds_dwordx4 v[174:175], off
	s_waitcnt vmcnt(8)
	s_waitcnt lgkmcnt(0)
	s_barrier
	s_setprio 1
	s_waitcnt lgkmcnt(0)
	v_mfma_f32_16x16x32_bf16 v[128:131], v[138:141], v[180:183], v[128:131]
	v_mfma_f32_16x16x32_bf16 v[128:131], v[142:145], v[184:187], v[128:131]
	v_mfma_f32_16x16x32_bf16 v[124:127], v[150:153], v[180:183], v[124:127]
	v_mfma_f32_16x16x32_bf16 v[124:127], v[154:157], v[184:187], v[124:127]
	v_mfma_f32_16x16x32_bf16 v[112:115], v[138:141], v[188:191], v[112:115]
	v_mfma_f32_16x16x32_bf16 v[112:115], v[142:145], v[192:195], v[112:115]
	v_mfma_f32_16x16x32_bf16 v[108:111], v[150:153], v[188:191], v[108:111]
	v_mfma_f32_16x16x32_bf16 v[108:111], v[154:157], v[192:195], v[108:111]
	v_mfma_f32_16x16x32_bf16 v[96:99], v[138:141], v[196:199], v[96:99]
	v_mfma_f32_16x16x32_bf16 v[96:99], v[142:145], v[206:209], v[96:99]
	v_mfma_f32_16x16x32_bf16 v[92:95], v[150:153], v[196:199], v[92:95]
	v_mfma_f32_16x16x32_bf16 v[92:95], v[154:157], v[206:209], v[92:95]
	v_mfma_f32_16x16x32_bf16 v[80:83], v[138:141], v[210:213], v[80:83]
	v_mfma_f32_16x16x32_bf16 v[80:83], v[142:145], v[214:217], v[80:83]
	v_mfma_f32_16x16x32_bf16 v[76:79], v[150:153], v[210:213], v[76:79]
	v_mfma_f32_16x16x32_bf16 v[76:79], v[154:157], v[214:217], v[76:79]
	s_setprio 0
	s_setprio 1
	v_mfma_f32_16x16x32_bf16 v[120:123], v[158:161], v[180:183], v[120:123]
	v_mfma_f32_16x16x32_bf16 v[120:123], v[162:165], v[184:187], v[120:123]
	v_mfma_f32_16x16x32_bf16 v[116:119], v[166:169], v[180:183], v[116:119]
	v_mfma_f32_16x16x32_bf16 v[116:119], v[170:173], v[184:187], v[116:119]
	v_mfma_f32_16x16x32_bf16 v[104:107], v[158:161], v[188:191], v[104:107]
	v_mfma_f32_16x16x32_bf16 v[104:107], v[162:165], v[192:195], v[104:107]
	v_mfma_f32_16x16x32_bf16 v[100:103], v[166:169], v[188:191], v[100:103]
	v_mfma_f32_16x16x32_bf16 v[100:103], v[170:173], v[192:195], v[100:103]
	v_mfma_f32_16x16x32_bf16 v[88:91], v[158:161], v[196:199], v[88:91]
	v_mfma_f32_16x16x32_bf16 v[88:91], v[162:165], v[206:209], v[88:91]
	v_mfma_f32_16x16x32_bf16 v[84:87], v[166:169], v[196:199], v[84:87]
	v_mfma_f32_16x16x32_bf16 v[84:87], v[170:173], v[206:209], v[84:87]
	v_mfma_f32_16x16x32_bf16 v[72:75], v[158:161], v[210:213], v[72:75]
	v_mfma_f32_16x16x32_bf16 v[72:75], v[162:165], v[214:217], v[72:75]
	v_mfma_f32_16x16x32_bf16 v[68:71], v[166:169], v[210:213], v[68:71]
	v_mfma_f32_16x16x32_bf16 v[68:71], v[170:173], v[214:217], v[68:71]
	s_setprio 0
	s_barrier
	s_add_i32 s28, s72, s66
	v_lshl_add_u64 v[174:175], s[24:25], 0, v[132:133]
	s_mov_b32 m0, s28
	ds_read_b128 v[180:183], v148 offset:16384
	ds_read_b128 v[184:187], v148 offset:17408
	ds_read_b128 v[188:191], v148 offset:18432
	ds_read_b128 v[192:195], v148 offset:19456
	ds_read_b128 v[196:199], v148 offset:20480
	ds_read_b128 v[206:209], v148 offset:21504
	ds_read_b128 v[210:213], v148 offset:22528
	ds_read_b128 v[214:217], v148 offset:23552
	global_load_lds_dwordx4 v[174:175], off
	s_add_i32 m0, s28, 0x2000
	s_add_u32 s28, s24, 0x100000
	v_lshl_add_u64 v[218:219], s[24:25], 0, v[0:1]
	s_addc_u32 s29, s25, 0
	s_add_i32 s72, s73, s66
	global_load_lds_dwordx4 v[218:219], off
	v_lshl_add_u64 v[220:221], s[28:29], 0, v[132:133]
	s_mov_b32 m0, s72
	v_lshl_add_u64 v[222:223], s[62:63], 0, v[0:1]
	global_load_lds_dwordx4 v[220:221], off
	v_lshl_add_u64 v[220:221], s[28:29], 0, v[0:1]
	s_add_i32 m0, s72, 0x2000
	s_nop 0
	global_load_lds_dwordx4 v[220:221], off
	v_lshl_add_u64 v[220:221], s[62:63], 0, v[132:133]
	s_mov_b32 m0, s67
	s_nop 0
	global_load_lds_dwordx4 v[220:221], off
	s_mov_b32 m0, s68
	s_nop 0
	global_load_lds_dwordx4 v[222:223], off
	s_waitcnt vmcnt(8)
	s_waitcnt lgkmcnt(0)
	s_barrier
	s_setprio 1
	s_waitcnt lgkmcnt(0)
	v_mfma_f32_16x16x32_bf16 v[64:67], v[138:141], v[180:183], v[64:67]
	v_mfma_f32_16x16x32_bf16 v[64:67], v[142:145], v[184:187], v[64:67]
	v_mfma_f32_16x16x32_bf16 v[60:63], v[150:153], v[180:183], v[60:63]
	v_mfma_f32_16x16x32_bf16 v[60:63], v[154:157], v[184:187], v[60:63]
	v_mfma_f32_16x16x32_bf16 v[48:51], v[138:141], v[188:191], v[48:51]
	v_mfma_f32_16x16x32_bf16 v[48:51], v[142:145], v[192:195], v[48:51]
	v_mfma_f32_16x16x32_bf16 v[44:47], v[150:153], v[188:191], v[44:47]
	v_mfma_f32_16x16x32_bf16 v[44:47], v[154:157], v[192:195], v[44:47]
	v_mfma_f32_16x16x32_bf16 v[32:35], v[138:141], v[196:199], v[32:35]
	v_mfma_f32_16x16x32_bf16 v[32:35], v[142:145], v[206:209], v[32:35]
	v_mfma_f32_16x16x32_bf16 v[28:31], v[150:153], v[196:199], v[28:31]
	v_mfma_f32_16x16x32_bf16 v[28:31], v[154:157], v[206:209], v[28:31]
	v_mfma_f32_16x16x32_bf16 v[16:19], v[138:141], v[210:213], v[16:19]
	v_mfma_f32_16x16x32_bf16 v[16:19], v[142:145], v[214:217], v[16:19]
	v_mfma_f32_16x16x32_bf16 v[12:15], v[150:153], v[210:213], v[12:15]
	v_mfma_f32_16x16x32_bf16 v[12:15], v[154:157], v[214:217], v[12:15]
	s_setprio 0
	s_setprio 1
	v_mfma_f32_16x16x32_bf16 v[56:59], v[158:161], v[180:183], v[56:59]
	v_mfma_f32_16x16x32_bf16 v[56:59], v[162:165], v[184:187], v[56:59]
	v_mfma_f32_16x16x32_bf16 v[52:55], v[166:169], v[180:183], v[52:55]
	v_mfma_f32_16x16x32_bf16 v[52:55], v[170:173], v[184:187], v[52:55]
	v_mfma_f32_16x16x32_bf16 v[40:43], v[158:161], v[188:191], v[40:43]
	v_mfma_f32_16x16x32_bf16 v[40:43], v[162:165], v[192:195], v[40:43]
	v_mfma_f32_16x16x32_bf16 v[36:39], v[166:169], v[188:191], v[36:39]
	v_mfma_f32_16x16x32_bf16 v[36:39], v[170:173], v[192:195], v[36:39]
	v_mfma_f32_16x16x32_bf16 v[24:27], v[158:161], v[196:199], v[24:27]
	v_mfma_f32_16x16x32_bf16 v[24:27], v[162:165], v[206:209], v[24:27]
	v_mfma_f32_16x16x32_bf16 v[20:23], v[166:169], v[196:199], v[20:23]
	v_mfma_f32_16x16x32_bf16 v[20:23], v[170:173], v[206:209], v[20:23]
	v_mfma_f32_16x16x32_bf16 v[8:11], v[158:161], v[210:213], v[8:11]
	v_mfma_f32_16x16x32_bf16 v[8:11], v[162:165], v[214:217], v[8:11]
	v_mfma_f32_16x16x32_bf16 v[4:7], v[166:169], v[210:213], v[4:7]
	v_mfma_f32_16x16x32_bf16 v[4:7], v[170:173], v[214:217], v[4:7]
	s_setprio 0
	s_barrier
	s_add_i32 s72, 0, 0x18000
	v_add_u32_e32 v149, s72, v146
	s_add_i32 s73, 0, 0x1c000
	ds_read_b128 v[138:141], v149
	ds_read_b128 v[142:145], v149 offset:1024
	ds_read_b128 v[150:153], v149 offset:2048
	ds_read_b128 v[154:157], v149 offset:3072
	v_add_u32_e32 v149, s73, v146
	ds_read_b128 v[158:161], v149
	ds_read_b128 v[162:165], v149 offset:1024
	ds_read_b128 v[166:169], v149 offset:2048
	ds_read_b128 v[170:173], v149 offset:3072
	s_add_u32 s28, s62, 0x100000
	s_addc_u32 s29, s63, 0
	s_mov_b32 m0, s69
	v_lshl_add_u64 v[224:225], s[28:29], 0, v[132:133]
	ds_read_b128 v[180:183], v148 offset:32768
	ds_read_b128 v[184:187], v148 offset:33792
	ds_read_b128 v[188:191], v148 offset:34816
	ds_read_b128 v[192:195], v148 offset:35840
	ds_read_b128 v[196:199], v148 offset:36864
	ds_read_b128 v[206:209], v148 offset:37888
	ds_read_b128 v[210:213], v148 offset:38912
	ds_read_b128 v[214:217], v148 offset:39936
	global_load_lds_dwordx4 v[224:225], off
	v_lshl_add_u64 v[224:225], s[28:29], 0, v[0:1]
	s_mov_b32 m0, s70
	s_nop 0
	global_load_lds_dwordx4 v[224:225], off
	s_waitcnt vmcnt(8)
	s_waitcnt lgkmcnt(0)
	s_barrier
	s_setprio 1
	s_waitcnt lgkmcnt(0)
	v_mfma_f32_16x16x32_bf16 v[128:131], v[138:141], v[180:183], v[128:131]
	v_mfma_f32_16x16x32_bf16 v[128:131], v[142:145], v[184:187], v[128:131]
	v_mfma_f32_16x16x32_bf16 v[124:127], v[150:153], v[180:183], v[124:127]
	v_mfma_f32_16x16x32_bf16 v[124:127], v[154:157], v[184:187], v[124:127]
	v_mfma_f32_16x16x32_bf16 v[112:115], v[138:141], v[188:191], v[112:115]
	v_mfma_f32_16x16x32_bf16 v[112:115], v[142:145], v[192:195], v[112:115]
	v_mfma_f32_16x16x32_bf16 v[108:111], v[150:153], v[188:191], v[108:111]
	v_mfma_f32_16x16x32_bf16 v[108:111], v[154:157], v[192:195], v[108:111]
	v_mfma_f32_16x16x32_bf16 v[96:99], v[138:141], v[196:199], v[96:99]
	v_mfma_f32_16x16x32_bf16 v[96:99], v[142:145], v[206:209], v[96:99]
	v_mfma_f32_16x16x32_bf16 v[92:95], v[150:153], v[196:199], v[92:95]
	v_mfma_f32_16x16x32_bf16 v[92:95], v[154:157], v[206:209], v[92:95]
	v_mfma_f32_16x16x32_bf16 v[80:83], v[138:141], v[210:213], v[80:83]
	v_mfma_f32_16x16x32_bf16 v[80:83], v[142:145], v[214:217], v[80:83]
	v_mfma_f32_16x16x32_bf16 v[76:79], v[150:153], v[210:213], v[76:79]
	v_mfma_f32_16x16x32_bf16 v[76:79], v[154:157], v[214:217], v[76:79]
	s_setprio 0
	s_setprio 1
	v_mfma_f32_16x16x32_bf16 v[120:123], v[158:161], v[180:183], v[120:123]
	v_mfma_f32_16x16x32_bf16 v[120:123], v[162:165], v[184:187], v[120:123]
	v_mfma_f32_16x16x32_bf16 v[116:119], v[166:169], v[180:183], v[116:119]
	v_mfma_f32_16x16x32_bf16 v[116:119], v[170:173], v[184:187], v[116:119]
	v_mfma_f32_16x16x32_bf16 v[104:107], v[158:161], v[188:191], v[104:107]
	v_mfma_f32_16x16x32_bf16 v[104:107], v[162:165], v[192:195], v[104:107]
	v_mfma_f32_16x16x32_bf16 v[100:103], v[166:169], v[188:191], v[100:103]
	v_mfma_f32_16x16x32_bf16 v[100:103], v[170:173], v[192:195], v[100:103]
	v_mfma_f32_16x16x32_bf16 v[88:91], v[158:161], v[196:199], v[88:91]
	v_mfma_f32_16x16x32_bf16 v[88:91], v[162:165], v[206:209], v[88:91]
	v_mfma_f32_16x16x32_bf16 v[84:87], v[166:169], v[196:199], v[84:87]
	v_mfma_f32_16x16x32_bf16 v[84:87], v[170:173], v[206:209], v[84:87]
	v_mfma_f32_16x16x32_bf16 v[72:75], v[158:161], v[210:213], v[72:75]
	v_mfma_f32_16x16x32_bf16 v[72:75], v[162:165], v[214:217], v[72:75]
	v_mfma_f32_16x16x32_bf16 v[68:71], v[166:169], v[210:213], v[68:71]
	v_mfma_f32_16x16x32_bf16 v[68:71], v[170:173], v[214:217], v[68:71]
	s_setprio 0
	s_barrier
	s_add_i32 s28, s72, s66
	v_lshl_add_u64 v[174:175], v[174:175], 0, s[30:31]
	s_mov_b32 m0, s28
	ds_read_b128 v[180:183], v148 offset:49152
	ds_read_b128 v[184:187], v148 offset:50176
	ds_read_b128 v[188:191], v148 offset:51200
	ds_read_b128 v[192:195], v148 offset:52224
	ds_read_b128 v[196:199], v148 offset:53248
	ds_read_b128 v[206:209], v148 offset:54272
	ds_read_b128 v[210:213], v148 offset:55296
	ds_read_b128 v[214:217], v148 offset:56320
	global_load_lds_dwordx4 v[174:175], off
	s_add_i32 m0, s28, 0x2000
	s_add_u32 s24, s24, 0x100080
	v_lshl_add_u64 v[174:175], v[218:219], 0, s[30:31]
	s_addc_u32 s25, s25, 0
	s_add_i32 s28, s73, s66
	global_load_lds_dwordx4 v[174:175], off
	v_lshl_add_u64 v[174:175], s[24:25], 0, v[132:133]
	s_mov_b32 m0, s28
	s_nop 0
	global_load_lds_dwordx4 v[174:175], off
	v_lshl_add_u64 v[174:175], s[24:25], 0, v[0:1]
	s_add_i32 m0, s28, 0x2000
	s_nop 0
	global_load_lds_dwordx4 v[174:175], off
	v_lshl_add_u64 v[174:175], v[220:221], 0, s[30:31]
	s_mov_b32 m0, s71
	s_nop 0
	global_load_lds_dwordx4 v[174:175], off
	v_lshl_add_u64 v[174:175], v[222:223], 0, s[30:31]
	s_mov_b32 m0, s84
	s_nop 0
	global_load_lds_dwordx4 v[174:175], off
	s_waitcnt vmcnt(8)
	s_waitcnt lgkmcnt(0)
	s_barrier
	s_setprio 1
	s_waitcnt lgkmcnt(0)
	v_mfma_f32_16x16x32_bf16 v[64:67], v[138:141], v[180:183], v[64:67]
	v_mfma_f32_16x16x32_bf16 v[64:67], v[142:145], v[184:187], v[64:67]
	v_mfma_f32_16x16x32_bf16 v[60:63], v[150:153], v[180:183], v[60:63]
	v_mfma_f32_16x16x32_bf16 v[60:63], v[154:157], v[184:187], v[60:63]
	v_mfma_f32_16x16x32_bf16 v[48:51], v[138:141], v[188:191], v[48:51]
	v_mfma_f32_16x16x32_bf16 v[48:51], v[142:145], v[192:195], v[48:51]
	v_mfma_f32_16x16x32_bf16 v[44:47], v[150:153], v[188:191], v[44:47]
	v_mfma_f32_16x16x32_bf16 v[44:47], v[154:157], v[192:195], v[44:47]
	v_mfma_f32_16x16x32_bf16 v[32:35], v[138:141], v[196:199], v[32:35]
	v_mfma_f32_16x16x32_bf16 v[32:35], v[142:145], v[206:209], v[32:35]
	v_mfma_f32_16x16x32_bf16 v[28:31], v[150:153], v[196:199], v[28:31]
	v_mfma_f32_16x16x32_bf16 v[28:31], v[154:157], v[206:209], v[28:31]
	v_mfma_f32_16x16x32_bf16 v[16:19], v[138:141], v[210:213], v[16:19]
	v_mfma_f32_16x16x32_bf16 v[16:19], v[142:145], v[214:217], v[16:19]
	v_mfma_f32_16x16x32_bf16 v[12:15], v[150:153], v[210:213], v[12:15]
	v_mfma_f32_16x16x32_bf16 v[12:15], v[154:157], v[214:217], v[12:15]
	s_setprio 0
	s_setprio 1
	v_mfma_f32_16x16x32_bf16 v[56:59], v[158:161], v[180:183], v[56:59]
	v_mfma_f32_16x16x32_bf16 v[56:59], v[162:165], v[184:187], v[56:59]
	v_mfma_f32_16x16x32_bf16 v[52:55], v[166:169], v[180:183], v[52:55]
	v_mfma_f32_16x16x32_bf16 v[52:55], v[170:173], v[184:187], v[52:55]
	v_mfma_f32_16x16x32_bf16 v[40:43], v[158:161], v[188:191], v[40:43]
	v_mfma_f32_16x16x32_bf16 v[40:43], v[162:165], v[192:195], v[40:43]
	v_mfma_f32_16x16x32_bf16 v[36:39], v[166:169], v[188:191], v[36:39]
	v_mfma_f32_16x16x32_bf16 v[36:39], v[170:173], v[192:195], v[36:39]
	v_mfma_f32_16x16x32_bf16 v[24:27], v[158:161], v[196:199], v[24:27]
	v_mfma_f32_16x16x32_bf16 v[24:27], v[162:165], v[206:209], v[24:27]
	v_mfma_f32_16x16x32_bf16 v[20:23], v[166:169], v[196:199], v[20:23]
	v_mfma_f32_16x16x32_bf16 v[20:23], v[170:173], v[206:209], v[20:23]
	v_mfma_f32_16x16x32_bf16 v[8:11], v[158:161], v[210:213], v[8:11]
	v_mfma_f32_16x16x32_bf16 v[8:11], v[162:165], v[214:217], v[8:11]
	v_mfma_f32_16x16x32_bf16 v[4:7], v[166:169], v[210:213], v[4:7]
	v_mfma_f32_16x16x32_bf16 v[4:7], v[170:173], v[214:217], v[4:7]
	s_setprio 0
	s_barrier
	s_add_i32 s92, s92, 2
	s_add_u32 s90, s90, 0x100
	s_addc_u32 s91, s91, 0
	s_cmp_gt_u32 s92, 61
	s_mov_b64 s[28:29], s[60:61]
	s_cbranch_scc0 .LBB0_961
	s_and_b64 vcc, exec, s[50:51]
	s_cbranch_vccz .LBB0_964
	s_barrier
